# SWIGLU epilogue H stores marked nt (streaming) to keep GEMM operands in L2
# baseline (speedup 1.0000x reference)
; __device__ __forceinline__ float sigmoidf_(float x) { return __builtin_amdgcn_rcpf(1.f + __expf(-x)); }
; __device__ __forceinline__ float rstd_of(float ssv) { return rsqrtf(ssv * (1.f / 1024.f) + EPS); }
; template <int EPI>
; __device__ __forceinline__ void gemm_epilogue(const f32x4 (&acc)[2][2][4][2], const Unit& u, int wr, int wc, int fr, int fq,
;                                               const EpiArgs& ea, const float (&rs_pre)[2][4]) {
;     ...
; #pragma unroll
;     for (int ai = 0; ai < 2; ++ai)
; #pragma unroll
;       for (int m = 0; m < 4; ++m) rsr[ai][m] = rstd_of(rsr[ai][m]);
;   }
;   if constexpr (EPI == EPI_SWIGLU) {
; #pragma unroll
;     for (int ai = 0; ai < 2; ++ai)
; #pragma unroll
;       for (int m = 0; m < 4; ++m) {
;         const int row = row0 + ai * 128 + m * 16;
;         const float rs = rsr[ai][m];
;         u16* rowp = ea.out_bf + (size_t)row * 2816 + u.pn * 128 + wc * 32 + 8 * fq;
;         uint2 hp2[2];
; #pragma unroll
;         for (int n = 0; n < 2; ++n) {
;           f32x4 g = acc[ai][0][m][n] * rs, uu = acc[ai][1][m][n] * rs, h;
; #pragma unroll
;           for (int i = 0; i < 4; ++i) h[i] = g[i] * sigmoidf_(g[i]) * uu[i];
;           hp2[n] = pack4(h);
;         }
;         *reinterpret_cast<uint4*>(rowp) = make_uint4(hp2[0].x, hp2[0].y, hp2[1].x, hp2[1].y);
;       }
.LBB0_918:
	v_fmamk_f32 v162, v149, 0x3a800000, v218
	v_fmamk_f32 v163, v148, 0x3a800000, v218
	v_fmamk_f32 v164, v147, 0x3a800000, v218
	v_fmamk_f32 v165, v146, 0x3a800000, v218
	v_fmamk_f32 v166, v143, 0x3a800000, v218
	v_fmamk_f32 v167, v142, 0x3a800000, v218
	v_fmamk_f32 v168, v141, 0x3a800000, v218
	v_fmamk_f32 v169, v140, 0x3a800000, v218
	v_rsq_f32_e32 v162, v162
	v_rsq_f32_e32 v163, v163
	v_rsq_f32_e32 v164, v164
	v_rsq_f32_e32 v165, v165
	v_rsq_f32_e32 v166, v166
	v_rsq_f32_e32 v167, v167
	v_rsq_f32_e32 v168, v168
	v_rsq_f32_e32 v169, v169
	v_lshl_add_u32 v148, s64, 8, v113
	s_lshl_b32 s36, s72, 7
	s_ashr_i32 s37, s36, 31
	s_lshl_b64 s[60:61], s[36:37], 1
	v_readlane_b32 s12, v254, 16
	s_lshl_b32 s94, s12, 1
	v_mul_lo_u32 v160, v148, s3
	v_add_u32_e32 v160, s60, v160
	v_add_u32_e32 v160, s94, v160
	v_add_u32_e32 v160, v160, v138
	v_mul_f32_e32 v170, 0xbfb8aa3b, v162
	v_mul_f32_e32 v172, v162, v162
	v_pk_mul_f32 v[174:175], v[126:127], v[170:171] op_sel_hi:[1,0]
	v_pk_mul_f32 v[176:177], v[128:129], v[170:171] op_sel_hi:[1,0]
	v_exp_f32_e32 v174, v174
	v_exp_f32_e32 v176, v176
	v_exp_f32_e32 v175, v175
	v_exp_f32_e32 v177, v177
	v_pk_mul_f32 v[122:123], v[126:127], v[122:123]
	v_pk_mul_f32 v[124:125], v[128:129], v[124:125]
	v_pk_add_f32 v[174:175], v[174:175], 1.0 op_sel_hi:[1,0]
	v_pk_add_f32 v[176:177], v[176:177], 1.0 op_sel_hi:[1,0]
	v_rcp_f32_e32 v174, v174
	v_rcp_f32_e32 v176, v176
	v_rcp_f32_e32 v175, v175
	v_rcp_f32_e32 v177, v177
	v_pk_mul_f32 v[174:175], v[174:175], v[172:173] op_sel_hi:[1,0]
	v_pk_mul_f32 v[176:177], v[176:177], v[172:173] op_sel_hi:[1,0]
	v_pk_mul_f32 v[126:127], v[122:123], v[174:175]
	v_pk_mul_f32 v[128:129], v[124:125], v[176:177]
	v_pk_mul_f32 v[174:175], v[118:119], v[170:171] op_sel_hi:[1,0]
	v_pk_mul_f32 v[176:177], v[120:121], v[170:171] op_sel_hi:[1,0]
	v_exp_f32_e32 v174, v174
	v_exp_f32_e32 v176, v176
	v_exp_f32_e32 v175, v175
	v_exp_f32_e32 v177, v177
	v_pk_mul_f32 v[114:115], v[118:119], v[114:115]
	v_pk_mul_f32 v[116:117], v[120:121], v[116:117]
	v_pk_add_f32 v[174:175], v[174:175], 1.0 op_sel_hi:[1,0]
	v_pk_add_f32 v[176:177], v[176:177], 1.0 op_sel_hi:[1,0]
	v_rcp_f32_e32 v174, v174
	v_rcp_f32_e32 v176, v176
	v_rcp_f32_e32 v175, v175
	v_rcp_f32_e32 v177, v177
	v_pk_mul_f32 v[174:175], v[174:175], v[172:173] op_sel_hi:[1,0]
	v_pk_mul_f32 v[176:177], v[176:177], v[172:173] op_sel_hi:[1,0]
	v_pk_mul_f32 v[118:119], v[114:115], v[174:175]
	v_pk_mul_f32 v[120:121], v[116:117], v[176:177]
	v_cvt_pk_bf16_f32 v126, v126, v127
	v_cvt_pk_bf16_f32 v127, v128, v129
	v_cvt_pk_bf16_f32 v128, v118, v119
	v_cvt_pk_bf16_f32 v129, v120, v121
	global_store_dwordx4 v160, v[126:129], s[42:43] nt
	v_mul_f32_e32 v170, 0xbfb8aa3b, v163
	v_mul_f32_e32 v172, v163, v163
	v_pk_mul_f32 v[174:175], v[108:109], v[170:171] op_sel_hi:[1,0]
	v_pk_mul_f32 v[176:177], v[110:111], v[170:171] op_sel_hi:[1,0]
	v_exp_f32_e32 v174, v174
	v_exp_f32_e32 v176, v176
	v_exp_f32_e32 v175, v175
	v_exp_f32_e32 v177, v177
	v_pk_mul_f32 v[104:105], v[108:109], v[104:105]
	v_pk_mul_f32 v[106:107], v[110:111], v[106:107]
	v_pk_add_f32 v[174:175], v[174:175], 1.0 op_sel_hi:[1,0]
	v_pk_add_f32 v[176:177], v[176:177], 1.0 op_sel_hi:[1,0]
	v_rcp_f32_e32 v174, v174
	v_rcp_f32_e32 v176, v176
	v_rcp_f32_e32 v175, v175
	v_rcp_f32_e32 v177, v177
	v_pk_mul_f32 v[174:175], v[174:175], v[172:173] op_sel_hi:[1,0]
	v_pk_mul_f32 v[176:177], v[176:177], v[172:173] op_sel_hi:[1,0]
	v_pk_mul_f32 v[108:109], v[104:105], v[174:175]
	v_pk_mul_f32 v[110:111], v[106:107], v[176:177]
	v_pk_mul_f32 v[174:175], v[100:101], v[170:171] op_sel_hi:[1,0]
	v_pk_mul_f32 v[176:177], v[102:103], v[170:171] op_sel_hi:[1,0]
	v_exp_f32_e32 v174, v174
	v_exp_f32_e32 v176, v176
	v_exp_f32_e32 v175, v175
	v_exp_f32_e32 v177, v177
	v_pk_mul_f32 v[96:97], v[100:101], v[96:97]
	v_pk_mul_f32 v[98:99], v[102:103], v[98:99]
	v_pk_add_f32 v[174:175], v[174:175], 1.0 op_sel_hi:[1,0]
	v_pk_add_f32 v[176:177], v[176:177], 1.0 op_sel_hi:[1,0]
	v_rcp_f32_e32 v174, v174
	v_rcp_f32_e32 v176, v176
	v_rcp_f32_e32 v175, v175
	v_rcp_f32_e32 v177, v177
	v_pk_mul_f32 v[174:175], v[174:175], v[172:173] op_sel_hi:[1,0]
	v_pk_mul_f32 v[176:177], v[176:177], v[172:173] op_sel_hi:[1,0]
	v_pk_mul_f32 v[100:101], v[96:97], v[174:175]
	v_pk_mul_f32 v[102:103], v[98:99], v[176:177]
	v_cvt_pk_bf16_f32 v108, v108, v109
	v_cvt_pk_bf16_f32 v109, v110, v111
	v_cvt_pk_bf16_f32 v110, v100, v101
	v_cvt_pk_bf16_f32 v111, v102, v103
	s_mul_i32 s37, s3, 16
	v_add_u32_e32 v161, s37, v160
	global_store_dwordx4 v161, v[108:111], s[42:43] nt
	v_mul_f32_e32 v170, 0xbfb8aa3b, v164
	v_mul_f32_e32 v172, v164, v164
	v_pk_mul_f32 v[174:175], v[92:93], v[170:171] op_sel_hi:[1,0]
	v_pk_mul_f32 v[176:177], v[94:95], v[170:171] op_sel_hi:[1,0]
	v_exp_f32_e32 v174, v174
	v_exp_f32_e32 v176, v176
	v_exp_f32_e32 v175, v175
	v_exp_f32_e32 v177, v177
	v_pk_mul_f32 v[88:89], v[92:93], v[88:89]
	v_pk_mul_f32 v[90:91], v[94:95], v[90:91]
	v_pk_add_f32 v[174:175], v[174:175], 1.0 op_sel_hi:[1,0]
	v_pk_add_f32 v[176:177], v[176:177], 1.0 op_sel_hi:[1,0]
	v_rcp_f32_e32 v174, v174
	v_rcp_f32_e32 v176, v176
	v_rcp_f32_e32 v175, v175
	v_rcp_f32_e32 v177, v177
	v_pk_mul_f32 v[174:175], v[174:175], v[172:173] op_sel_hi:[1,0]
	v_pk_mul_f32 v[176:177], v[176:177], v[172:173] op_sel_hi:[1,0]
	v_pk_mul_f32 v[92:93], v[88:89], v[174:175]
	v_pk_mul_f32 v[94:95], v[90:91], v[176:177]
	v_pk_mul_f32 v[174:175], v[84:85], v[170:171] op_sel_hi:[1,0]
	v_pk_mul_f32 v[176:177], v[86:87], v[170:171] op_sel_hi:[1,0]
	v_exp_f32_e32 v174, v174
	v_exp_f32_e32 v176, v176
	v_exp_f32_e32 v175, v175
	v_exp_f32_e32 v177, v177
	v_pk_mul_f32 v[80:81], v[84:85], v[80:81]
; __device__ __forceinline__ float sigmoidf_(float x) { return __builtin_amdgcn_rcpf(1.f + __expf(-x)); }
; template <int EPI>
; __device__ __forceinline__ void gemm_epilogue(const f32x4 (&acc)[2][2][4][2], const Unit& u, int wr, int wc, int fr, int fq,
;                                               const EpiArgs& ea, const float (&rs_pre)[2][4]) {
;     ...
;   if constexpr (EPI == EPI_SWIGLU) {
; #pragma unroll
;     for (int ai = 0; ai < 2; ++ai)
; #pragma unroll
;       for (int m = 0; m < 4; ++m) {
;         const int row = row0 + ai * 128 + m * 16;
;         const float rs = rsr[ai][m];
;         u16* rowp = ea.out_bf + (size_t)row * 2816 + u.pn * 128 + wc * 32 + 8 * fq;
;         uint2 hp2[2];
; #pragma unroll
;         for (int n = 0; n < 2; ++n) {
;           f32x4 g = acc[ai][0][m][n] * rs, uu = acc[ai][1][m][n] * rs, h;
; #pragma unroll
;           for (int i = 0; i < 4; ++i) h[i] = g[i] * sigmoidf_(g[i]) * uu[i];
;           hp2[n] = pack4(h);
;         }
;         *reinterpret_cast<uint4*>(rowp) = make_uint4(hp2[0].x, hp2[0].y, hp2[1].x, hp2[1].y);
;       }
	v_pk_mul_f32 v[82:83], v[86:87], v[82:83]
	v_pk_add_f32 v[174:175], v[174:175], 1.0 op_sel_hi:[1,0]
	v_pk_add_f32 v[176:177], v[176:177], 1.0 op_sel_hi:[1,0]
	v_rcp_f32_e32 v174, v174
	v_rcp_f32_e32 v176, v176
	v_rcp_f32_e32 v175, v175
	v_rcp_f32_e32 v177, v177
	v_pk_mul_f32 v[174:175], v[174:175], v[172:173] op_sel_hi:[1,0]
	v_pk_mul_f32 v[176:177], v[176:177], v[172:173] op_sel_hi:[1,0]
	v_pk_mul_f32 v[84:85], v[80:81], v[174:175]
	v_pk_mul_f32 v[86:87], v[82:83], v[176:177]
	v_cvt_pk_bf16_f32 v92, v92, v93
	v_cvt_pk_bf16_f32 v93, v94, v95
	v_cvt_pk_bf16_f32 v94, v84, v85
	v_cvt_pk_bf16_f32 v95, v86, v87
	s_mul_i32 s37, s3, 32
	v_add_u32_e32 v161, s37, v160
	global_store_dwordx4 v161, v[92:95], s[42:43] nt
	v_mul_f32_e32 v170, 0xbfb8aa3b, v165
	v_mul_f32_e32 v172, v165, v165
	v_pk_mul_f32 v[174:175], v[76:77], v[170:171] op_sel_hi:[1,0]
	v_pk_mul_f32 v[176:177], v[78:79], v[170:171] op_sel_hi:[1,0]
	v_exp_f32_e32 v174, v174
	v_exp_f32_e32 v176, v176
	v_exp_f32_e32 v175, v175
	v_exp_f32_e32 v177, v177
	v_pk_mul_f32 v[72:73], v[76:77], v[72:73]
	v_pk_mul_f32 v[74:75], v[78:79], v[74:75]
	v_pk_add_f32 v[174:175], v[174:175], 1.0 op_sel_hi:[1,0]
	v_pk_add_f32 v[176:177], v[176:177], 1.0 op_sel_hi:[1,0]
	v_rcp_f32_e32 v174, v174
	v_rcp_f32_e32 v176, v176
	v_rcp_f32_e32 v175, v175
	v_rcp_f32_e32 v177, v177
	v_pk_mul_f32 v[174:175], v[174:175], v[172:173] op_sel_hi:[1,0]
	v_pk_mul_f32 v[176:177], v[176:177], v[172:173] op_sel_hi:[1,0]
	v_pk_mul_f32 v[76:77], v[72:73], v[174:175]
	v_pk_mul_f32 v[78:79], v[74:75], v[176:177]
	v_pk_mul_f32 v[174:175], v[68:69], v[170:171] op_sel_hi:[1,0]
	v_pk_mul_f32 v[176:177], v[70:71], v[170:171] op_sel_hi:[1,0]
	v_exp_f32_e32 v174, v174
	v_exp_f32_e32 v176, v176
	v_exp_f32_e32 v175, v175
	v_exp_f32_e32 v177, v177
	v_pk_mul_f32 v[64:65], v[68:69], v[64:65]
	v_pk_mul_f32 v[66:67], v[70:71], v[66:67]
	v_pk_add_f32 v[174:175], v[174:175], 1.0 op_sel_hi:[1,0]
	v_pk_add_f32 v[176:177], v[176:177], 1.0 op_sel_hi:[1,0]
	v_rcp_f32_e32 v174, v174
	v_rcp_f32_e32 v176, v176
	v_rcp_f32_e32 v175, v175
	v_rcp_f32_e32 v177, v177
	v_pk_mul_f32 v[174:175], v[174:175], v[172:173] op_sel_hi:[1,0]
	v_pk_mul_f32 v[176:177], v[176:177], v[172:173] op_sel_hi:[1,0]
	v_pk_mul_f32 v[68:69], v[64:65], v[174:175]
	v_pk_mul_f32 v[70:71], v[66:67], v[176:177]
	v_cvt_pk_bf16_f32 v76, v76, v77
	v_cvt_pk_bf16_f32 v77, v78, v79
	v_cvt_pk_bf16_f32 v78, v68, v69
	v_cvt_pk_bf16_f32 v79, v70, v71
	s_mul_i32 s37, s3, 48
	v_add_u32_e32 v161, s37, v160
	global_store_dwordx4 v161, v[76:79], s[42:43] nt
	v_mul_f32_e32 v170, 0xbfb8aa3b, v166
	v_mul_f32_e32 v172, v166, v166
	v_pk_mul_f32 v[174:175], v[60:61], v[170:171] op_sel_hi:[1,0]
	v_pk_mul_f32 v[176:177], v[62:63], v[170:171] op_sel_hi:[1,0]
	v_exp_f32_e32 v174, v174
	v_exp_f32_e32 v176, v176
	v_exp_f32_e32 v175, v175
	v_exp_f32_e32 v177, v177
	v_pk_mul_f32 v[56:57], v[60:61], v[56:57]
	v_pk_mul_f32 v[58:59], v[62:63], v[58:59]
	v_pk_add_f32 v[174:175], v[174:175], 1.0 op_sel_hi:[1,0]
	v_pk_add_f32 v[176:177], v[176:177], 1.0 op_sel_hi:[1,0]
	v_rcp_f32_e32 v174, v174
	v_rcp_f32_e32 v176, v176
	v_rcp_f32_e32 v175, v175
	v_rcp_f32_e32 v177, v177
	v_pk_mul_f32 v[174:175], v[174:175], v[172:173] op_sel_hi:[1,0]
	v_pk_mul_f32 v[176:177], v[176:177], v[172:173] op_sel_hi:[1,0]
	v_pk_mul_f32 v[60:61], v[56:57], v[174:175]
	v_pk_mul_f32 v[62:63], v[58:59], v[176:177]
	v_pk_mul_f32 v[174:175], v[52:53], v[170:171] op_sel_hi:[1,0]
	v_pk_mul_f32 v[176:177], v[54:55], v[170:171] op_sel_hi:[1,0]
	v_exp_f32_e32 v174, v174
	v_exp_f32_e32 v176, v176
	v_exp_f32_e32 v175, v175
	v_exp_f32_e32 v177, v177
	v_pk_mul_f32 v[48:49], v[52:53], v[48:49]
	v_pk_mul_f32 v[50:51], v[54:55], v[50:51]
	v_pk_add_f32 v[174:175], v[174:175], 1.0 op_sel_hi:[1,0]
	v_pk_add_f32 v[176:177], v[176:177], 1.0 op_sel_hi:[1,0]
	v_rcp_f32_e32 v174, v174
	v_rcp_f32_e32 v176, v176
	v_rcp_f32_e32 v175, v175
	v_rcp_f32_e32 v177, v177
	v_pk_mul_f32 v[174:175], v[174:175], v[172:173] op_sel_hi:[1,0]
	v_pk_mul_f32 v[176:177], v[176:177], v[172:173] op_sel_hi:[1,0]
	v_pk_mul_f32 v[52:53], v[48:49], v[174:175]
	v_pk_mul_f32 v[54:55], v[50:51], v[176:177]
	v_cvt_pk_bf16_f32 v60, v60, v61
	v_cvt_pk_bf16_f32 v61, v62, v63
	v_cvt_pk_bf16_f32 v62, v52, v53
	v_cvt_pk_bf16_f32 v63, v54, v55
	s_mul_i32 s37, s3, 128
	v_add_u32_e32 v161, s37, v160
	global_store_dwordx4 v161, v[60:63], s[42:43] nt
	v_mul_f32_e32 v170, 0xbfb8aa3b, v167
	v_mul_f32_e32 v172, v167, v167
	v_pk_mul_f32 v[174:175], v[44:45], v[170:171] op_sel_hi:[1,0]
	v_pk_mul_f32 v[176:177], v[46:47], v[170:171] op_sel_hi:[1,0]
	v_exp_f32_e32 v174, v174
	v_exp_f32_e32 v176, v176
	v_exp_f32_e32 v175, v175
	v_exp_f32_e32 v177, v177
	v_pk_mul_f32 v[40:41], v[44:45], v[40:41]
	v_pk_mul_f32 v[42:43], v[46:47], v[42:43]
	v_pk_add_f32 v[174:175], v[174:175], 1.0 op_sel_hi:[1,0]
	v_pk_add_f32 v[176:177], v[176:177], 1.0 op_sel_hi:[1,0]
	v_rcp_f32_e32 v174, v174
	v_rcp_f32_e32 v176, v176
	v_rcp_f32_e32 v175, v175
	v_rcp_f32_e32 v177, v177
	v_pk_mul_f32 v[174:175], v[174:175], v[172:173] op_sel_hi:[1,0]
	v_pk_mul_f32 v[176:177], v[176:177], v[172:173] op_sel_hi:[1,0]
	v_pk_mul_f32 v[44:45], v[40:41], v[174:175]
	v_pk_mul_f32 v[46:47], v[42:43], v[176:177]
; __device__ __forceinline__ float sigmoidf_(float x) { return __builtin_amdgcn_rcpf(1.f + __expf(-x)); }
; template <int EPI>
; __device__ __forceinline__ void gemm_epilogue(const f32x4 (&acc)[2][2][4][2], const Unit& u, int wr, int wc, int fr, int fq,
;                                               const EpiArgs& ea, const float (&rs_pre)[2][4]) {
;     ...
;   if constexpr (EPI == EPI_SWIGLU) {
; #pragma unroll
;     for (int ai = 0; ai < 2; ++ai)
; #pragma unroll
;       for (int m = 0; m < 4; ++m) {
;         const int row = row0 + ai * 128 + m * 16;
;         const float rs = rsr[ai][m];
;         u16* rowp = ea.out_bf + (size_t)row * 2816 + u.pn * 128 + wc * 32 + 8 * fq;
;         uint2 hp2[2];
; #pragma unroll
;         for (int n = 0; n < 2; ++n) {
;           f32x4 g = acc[ai][0][m][n] * rs, uu = acc[ai][1][m][n] * rs, h;
; #pragma unroll
;           for (int i = 0; i < 4; ++i) h[i] = g[i] * sigmoidf_(g[i]) * uu[i];
;           hp2[n] = pack4(h);
;         }
;         *reinterpret_cast<uint4*>(rowp) = make_uint4(hp2[0].x, hp2[0].y, hp2[1].x, hp2[1].y);
;       }
	v_pk_mul_f32 v[174:175], v[36:37], v[170:171] op_sel_hi:[1,0]
	v_pk_mul_f32 v[176:177], v[38:39], v[170:171] op_sel_hi:[1,0]
	v_exp_f32_e32 v174, v174
	v_exp_f32_e32 v176, v176
	v_exp_f32_e32 v175, v175
	v_exp_f32_e32 v177, v177
	v_pk_mul_f32 v[32:33], v[36:37], v[32:33]
	v_pk_mul_f32 v[34:35], v[38:39], v[34:35]
	v_pk_add_f32 v[174:175], v[174:175], 1.0 op_sel_hi:[1,0]
	v_pk_add_f32 v[176:177], v[176:177], 1.0 op_sel_hi:[1,0]
	v_rcp_f32_e32 v174, v174
	v_rcp_f32_e32 v176, v176
	v_rcp_f32_e32 v175, v175
	v_rcp_f32_e32 v177, v177
	v_pk_mul_f32 v[174:175], v[174:175], v[172:173] op_sel_hi:[1,0]
	v_pk_mul_f32 v[176:177], v[176:177], v[172:173] op_sel_hi:[1,0]
	v_pk_mul_f32 v[36:37], v[32:33], v[174:175]
	v_pk_mul_f32 v[38:39], v[34:35], v[176:177]
	v_cvt_pk_bf16_f32 v44, v44, v45
	v_cvt_pk_bf16_f32 v45, v46, v47
	v_cvt_pk_bf16_f32 v46, v36, v37
	v_cvt_pk_bf16_f32 v47, v38, v39
	s_mul_i32 s37, s3, 144
	v_add_u32_e32 v161, s37, v160
	global_store_dwordx4 v161, v[44:47], s[42:43] nt
	v_mul_f32_e32 v170, 0xbfb8aa3b, v168
	v_mul_f32_e32 v172, v168, v168
	v_pk_mul_f32 v[174:175], v[28:29], v[170:171] op_sel_hi:[1,0]
	v_pk_mul_f32 v[176:177], v[30:31], v[170:171] op_sel_hi:[1,0]
	v_exp_f32_e32 v174, v174
	v_exp_f32_e32 v176, v176
	v_exp_f32_e32 v175, v175
	v_exp_f32_e32 v177, v177
	v_pk_mul_f32 v[24:25], v[28:29], v[24:25]
	v_pk_mul_f32 v[26:27], v[30:31], v[26:27]
	v_pk_add_f32 v[174:175], v[174:175], 1.0 op_sel_hi:[1,0]
	v_pk_add_f32 v[176:177], v[176:177], 1.0 op_sel_hi:[1,0]
	v_rcp_f32_e32 v174, v174
	v_rcp_f32_e32 v176, v176
	v_rcp_f32_e32 v175, v175
	v_rcp_f32_e32 v177, v177
	v_pk_mul_f32 v[174:175], v[174:175], v[172:173] op_sel_hi:[1,0]
	v_pk_mul_f32 v[176:177], v[176:177], v[172:173] op_sel_hi:[1,0]
	v_pk_mul_f32 v[28:29], v[24:25], v[174:175]
	v_pk_mul_f32 v[30:31], v[26:27], v[176:177]
	v_pk_mul_f32 v[174:175], v[20:21], v[170:171] op_sel_hi:[1,0]
	v_pk_mul_f32 v[176:177], v[22:23], v[170:171] op_sel_hi:[1,0]
	v_exp_f32_e32 v174, v174
	v_exp_f32_e32 v176, v176
	v_exp_f32_e32 v175, v175
	v_exp_f32_e32 v177, v177
	v_pk_mul_f32 v[16:17], v[20:21], v[16:17]
	v_pk_mul_f32 v[18:19], v[22:23], v[18:19]
	v_pk_add_f32 v[174:175], v[174:175], 1.0 op_sel_hi:[1,0]
	v_pk_add_f32 v[176:177], v[176:177], 1.0 op_sel_hi:[1,0]
	v_rcp_f32_e32 v174, v174
	v_rcp_f32_e32 v176, v176
	v_rcp_f32_e32 v175, v175
	v_rcp_f32_e32 v177, v177
	v_pk_mul_f32 v[174:175], v[174:175], v[172:173] op_sel_hi:[1,0]
	v_pk_mul_f32 v[176:177], v[176:177], v[172:173] op_sel_hi:[1,0]
	v_pk_mul_f32 v[20:21], v[16:17], v[174:175]
	v_pk_mul_f32 v[22:23], v[18:19], v[176:177]
	v_cvt_pk_bf16_f32 v28, v28, v29
	v_cvt_pk_bf16_f32 v29, v30, v31
	v_cvt_pk_bf16_f32 v30, v20, v21
	v_cvt_pk_bf16_f32 v31, v22, v23
	s_mul_i32 s37, s3, 160
	v_add_u32_e32 v161, s37, v160
	global_store_dwordx4 v161, v[28:31], s[42:43] nt
	v_mul_f32_e32 v170, 0xbfb8aa3b, v169
	v_mul_f32_e32 v172, v169, v169
	v_pk_mul_f32 v[174:175], v[12:13], v[170:171] op_sel_hi:[1,0]
	v_pk_mul_f32 v[176:177], v[14:15], v[170:171] op_sel_hi:[1,0]
	v_exp_f32_e32 v174, v174
	v_exp_f32_e32 v176, v176
	v_exp_f32_e32 v175, v175
	v_exp_f32_e32 v177, v177
	v_pk_mul_f32 v[8:9], v[12:13], v[8:9]
	v_pk_mul_f32 v[10:11], v[14:15], v[10:11]
	v_pk_add_f32 v[174:175], v[174:175], 1.0 op_sel_hi:[1,0]
	v_pk_add_f32 v[176:177], v[176:177], 1.0 op_sel_hi:[1,0]
	v_rcp_f32_e32 v174, v174
	v_rcp_f32_e32 v176, v176
	v_rcp_f32_e32 v175, v175
	v_rcp_f32_e32 v177, v177
	v_pk_mul_f32 v[174:175], v[174:175], v[172:173] op_sel_hi:[1,0]
	v_pk_mul_f32 v[176:177], v[176:177], v[172:173] op_sel_hi:[1,0]
	v_pk_mul_f32 v[12:13], v[8:9], v[174:175]
	v_pk_mul_f32 v[14:15], v[10:11], v[176:177]
	v_pk_mul_f32 v[174:175], v[4:5], v[170:171] op_sel_hi:[1,0]
	v_pk_mul_f32 v[176:177], v[6:7], v[170:171] op_sel_hi:[1,0]
	v_exp_f32_e32 v174, v174
	v_exp_f32_e32 v176, v176
	v_exp_f32_e32 v175, v175
	v_exp_f32_e32 v177, v177
	v_pk_mul_f32 v[0:1], v[4:5], v[0:1]
	v_pk_mul_f32 v[2:3], v[6:7], v[2:3]
	v_pk_add_f32 v[174:175], v[174:175], 1.0 op_sel_hi:[1,0]
	v_pk_add_f32 v[176:177], v[176:177], 1.0 op_sel_hi:[1,0]
	v_rcp_f32_e32 v174, v174
	v_rcp_f32_e32 v176, v176
	v_rcp_f32_e32 v175, v175
	v_rcp_f32_e32 v177, v177
	v_pk_mul_f32 v[174:175], v[174:175], v[172:173] op_sel_hi:[1,0]
	v_pk_mul_f32 v[176:177], v[176:177], v[172:173] op_sel_hi:[1,0]
	v_pk_mul_f32 v[4:5], v[0:1], v[174:175]
	v_pk_mul_f32 v[6:7], v[2:3], v[176:177]
	v_cvt_pk_bf16_f32 v12, v12, v13
	v_cvt_pk_bf16_f32 v13, v14, v15
	v_cvt_pk_bf16_f32 v14, v4, v5
	v_cvt_pk_bf16_f32 v15, v6, v7
	s_mul_i32 s37, s3, 176
	v_add_u32_e32 v161, s37, v160
	global_store_dwordx4 v161, v[12:15], s[42:43] nt
	s_and_b64 vcc, exec, s[0:1]
	s_mov_b64 s[36:37], -1
	s_cbranch_vccnz .LBB0_903
	v_lshl_add_u32 v0, s71, 8, v113
	v_ashrrev_i32_e32 v1, 31, v0
	v_lshl_add_u64 v[0:1], v[0:1], 2, s[4:5]
	global_load_dword v149, v[0:1], off
	global_load_dword v148, v[0:1], off offset:64
	global_load_dword v147, v[0:1], off offset:128
	global_load_dword v146, v[0:1], off offset:192
	global_load_dword v143, v[0:1], off offset:512
	global_load_dword v142, v[0:1], off offset:576
	global_load_dword v141, v[0:1], off offset:640
	global_load_dword v140, v[0:1], off offset:704
	s_mov_b64 s[36:37], 0
	s_branch .LBB0_903
